# in-proj epilogue (q/k slices): rotary cos/sin rows of all four row blocks fetched at the head of the rotary path
# speedup vs baseline: 1.0341x; 1.0005x over previous
.LBB0_254:
	s_lshl_b32 s58, s42, 7
	v_add_u32_e32 v78, s58, v175
	v_cndmask_b32_e64 v76, 1.0, v231, s[4:5]
	s_and_b64 vcc, exec, s[0:1]
	s_cbranch_vccz .LBB0_258
	v_mov_b32_e32 v2, v78
	v_mul_hi_i32 v80, v2, s52
	v_lshrrev_b32_e32 v81, 31, v80
	v_ashrrev_i32_e32 v80, 11, v80
	v_add_u32_e32 v80, v80, v81
	v_mul_i32_i24_e32 v80, 0x1100, v80
	v_sub_u32_e32 v2, v2, v80
	v_cmp_lt_i32_e32 vcc, s53, v2
	v_mov_b32_e32 v116, 1.0
	v_mov_b32_e32 v117, 1.0
	v_mov_b32_e32 v118, 1.0
	v_mov_b32_e32 v119, 1.0
	v_mov_b32_e32 v120, 0
	v_mov_b32_e32 v121, 0
	v_mov_b32_e32 v122, 0
	v_mov_b32_e32 v123, 0
	s_and_saveexec_b64 s[0:1], vcc
	v_lshl_add_u32 v2, v2, 4, v232
	v_lshlrev_b64 v[80:81], 2, v[2:3]
	v_lshl_add_u64 v[118:119], v[0:1], 0, v[80:81]
	v_lshl_add_u64 v[120:121], v[132:133], 0, v[80:81]
	global_load_dwordx4 v[116:119], v[118:119], off
	global_load_dwordx4 v[120:123], v[120:121], off
	s_mov_b64 exec, s[0:1]
	v_or_b32_e32 v2, 16, v78
	v_mul_hi_i32 v80, v2, s52
	v_lshrrev_b32_e32 v81, 31, v80
	v_ashrrev_i32_e32 v80, 11, v80
	v_add_u32_e32 v80, v80, v81
	v_mul_i32_i24_e32 v80, 0x1100, v80
	v_sub_u32_e32 v2, v2, v80
	v_cmp_lt_i32_e32 vcc, s53, v2
	v_mov_b32_e32 v124, 1.0
	v_mov_b32_e32 v125, 1.0
	v_mov_b32_e32 v126, 1.0
	v_mov_b32_e32 v127, 1.0
	v_mov_b32_e32 v128, 0
	v_mov_b32_e32 v129, 0
	v_mov_b32_e32 v130, 0
	v_mov_b32_e32 v131, 0
	s_and_saveexec_b64 s[0:1], vcc
	v_lshl_add_u32 v2, v2, 4, v232
	v_lshlrev_b64 v[80:81], 2, v[2:3]
	v_lshl_add_u64 v[126:127], v[0:1], 0, v[80:81]
	v_lshl_add_u64 v[128:129], v[132:133], 0, v[80:81]
	global_load_dwordx4 v[124:127], v[126:127], off
	global_load_dwordx4 v[128:131], v[128:129], off
	s_mov_b64 exec, s[0:1]
	v_or_b32_e32 v2, 32, v78
	v_mul_hi_i32 v80, v2, s52
	v_lshrrev_b32_e32 v81, 31, v80
	v_ashrrev_i32_e32 v80, 11, v80
	v_add_u32_e32 v80, v80, v81
	v_mul_i32_i24_e32 v80, 0x1100, v80
	v_sub_u32_e32 v2, v2, v80
	v_cmp_lt_i32_e32 vcc, s53, v2
	v_mov_b32_e32 v152, 1.0
	v_mov_b32_e32 v153, 1.0
	v_mov_b32_e32 v154, 1.0
	v_mov_b32_e32 v155, 1.0
	v_mov_b32_e32 v156, 0
	v_mov_b32_e32 v157, 0
	v_mov_b32_e32 v158, 0
	v_mov_b32_e32 v159, 0
	s_and_saveexec_b64 s[0:1], vcc
	v_lshl_add_u32 v2, v2, 4, v232
	v_lshlrev_b64 v[80:81], 2, v[2:3]
	v_lshl_add_u64 v[154:155], v[0:1], 0, v[80:81]
	v_lshl_add_u64 v[156:157], v[132:133], 0, v[80:81]
	global_load_dwordx4 v[152:155], v[154:155], off
	global_load_dwordx4 v[156:159], v[156:157], off
	s_mov_b64 exec, s[0:1]
	v_or_b32_e32 v2, 48, v78
	v_mul_hi_i32 v80, v2, s52
	v_lshrrev_b32_e32 v81, 31, v80
	v_ashrrev_i32_e32 v80, 11, v80
	v_add_u32_e32 v80, v80, v81
	v_mul_i32_i24_e32 v80, 0x1100, v80
	v_sub_u32_e32 v2, v2, v80
	v_cmp_lt_i32_e32 vcc, s53, v2
	v_mov_b32_e32 v160, 1.0
	v_mov_b32_e32 v161, 1.0
	v_mov_b32_e32 v162, 1.0
	v_mov_b32_e32 v163, 1.0
	v_mov_b32_e32 v164, 0
	v_mov_b32_e32 v165, 0
	v_mov_b32_e32 v166, 0
	v_mov_b32_e32 v167, 0
	s_and_saveexec_b64 s[0:1], vcc
	v_lshl_add_u32 v2, v2, 4, v232
	v_lshlrev_b64 v[80:81], 2, v[2:3]
	v_lshl_add_u64 v[162:163], v[0:1], 0, v[80:81]
	v_lshl_add_u64 v[164:165], v[132:133], 0, v[80:81]
	global_load_dwordx4 v[160:163], v[162:163], off
	global_load_dwordx4 v[164:167], v[164:165], off
	s_mov_b64 exec, s[0:1]
	s_mov_b64 s[0:1], -1
	s_waitcnt vmcnt(0)
	v_mov_b32_e32 v68, v116
	v_mov_b32_e32 v69, v117
	v_mov_b32_e32 v70, v118
	v_mov_b32_e32 v71, v119
	v_mov_b32_e32 v72, v120
	v_mov_b32_e32 v73, v121
	v_mov_b32_e32 v74, v122
	v_mov_b32_e32 v75, v123

.LBB0_320:
	s_and_b64 vcc, exec, s[0:1]
	s_cbranch_vccz .LBB0_324
	s_waitcnt vmcnt(0)
	v_mov_b32_e32 v52, v124
	v_mov_b32_e32 v53, v125
	v_mov_b32_e32 v54, v126
	v_mov_b32_e32 v55, v127
	v_mov_b32_e32 v56, v128
	v_mov_b32_e32 v57, v129
	v_mov_b32_e32 v58, v130
	v_mov_b32_e32 v59, v131

.LBB0_386:
	s_and_b64 vcc, exec, s[0:1]
	s_cbranch_vccz .LBB0_390
	s_waitcnt vmcnt(0)
	v_mov_b32_e32 v36, v152
	v_mov_b32_e32 v37, v153
	v_mov_b32_e32 v38, v154
	v_mov_b32_e32 v39, v155
	v_mov_b32_e32 v40, v156
	v_mov_b32_e32 v41, v157
	v_mov_b32_e32 v42, v158
	v_mov_b32_e32 v43, v159

.LBB0_452:
	s_and_b64 vcc, exec, s[0:1]
	s_cbranch_vccz .LBB0_183
	s_waitcnt vmcnt(0)
	v_mov_b32_e32 v20, v160
	v_mov_b32_e32 v21, v161
	v_mov_b32_e32 v22, v162
	v_mov_b32_e32 v23, v163
	v_mov_b32_e32 v24, v164
	v_mov_b32_e32 v25, v165
	v_mov_b32_e32 v26, v166
	v_mov_b32_e32 v27, v167
	s_branch .LBB0_182
